# phase 2 dealing: prep/foxcum/compress workgroups take no later-round GEMM tiles (NSK 16 -> 280)
# baseline (speedup 1.0000x reference)
; DI void phase_prep(const Params& p, int L, char* smem) {
;     ...
;   for (int it0 = blockIdx.x; ; it0 += G) {
;     int it;
;     if (it0 < G) it = it0;
;     else { const int rnd = it0 / G, pos = it0 - rnd * G; if (pos < NSK) break; it = G + (rnd - 1) * (G - NSK) + (pos - NSK); }
;     if (it >= o5) break;
.LBB0_490:
	s_cmp_lt_i32 s33, s88
	s_cselect_b64 s[2:3], -1, 0
	s_and_b64 vcc, exec, s[2:3]
	s_cbranch_vccnz .LBB0_492
	s_abs_i32 s3, s33
	s_mul_hi_u32 s4, s3, s10
	s_mul_i32 s5, s4, s34
	s_ashr_i32 s2, s33, 31
	s_sub_i32 s3, s3, s5
	s_xor_b32 s2, s2, s11
	s_add_i32 s5, s4, 1
	s_sub_i32 s6, s3, s34
	s_cmp_ge_u32 s3, s34
	s_cselect_b32 s4, s5, s4
	s_cselect_b32 s3, s6, s3
	s_add_i32 s5, s4, 1
	s_cmp_ge_u32 s3, s34
	s_cselect_b32 s3, s5, s4
	s_xor_b32 s3, s3, s2
	s_sub_i32 s4, s3, s2
	s_mul_i32 s2, s4, s88
	s_sub_i32 s2, s33, s2
	s_cmpk_gt_i32 s2, 0x117
	s_cselect_b64 s[2:3], -1, 0
	s_mulk_i32 s4, 0x118
	s_sub_i32 s89, s33, s4
	s_andn2_b64 vcc, exec, s[2:3]
	s_mov_b64 s[2:3], 0
	s_cbranch_vccnz .LBB0_489
	s_branch .LBB0_493
